# attention work items: s_setprio 3 while a block runs a B (differential) item, 2 for C (MLA) items, default for A items (critical-path wave priority)
# baseline (speedup 1.0000x reference)
;     ...
;   for (;;) {
;     const int item = next_item(p.counters + ((cset * 4 + l) * 3 + 0) * 8 + xcd, s_item, tid);
;     if (item >= 128) break;
.LBB0_515:
	s_setprio 0
	s_and_b64 vcc, exec, s[0:1]
	s_cbranch_vccnz .LBB0_549

;     ...
;     const int item = next_item(p.counters + ((cset * 4 + l) * 3 + 0) * 8 + xcd, s_item, tid);
;     if (item >= 128) break;
;     const int qb = 63 - (item >> 1), mp = item & 1;
;     const int b = xcd >> 2, h = xcd & 3;
;     for (int i = tid; i < 2048; i += NTHREADS) bias_lds[i] = p.biasB2[h * 2048 + i];
.LBB0_520:
	s_or_b64 exec, exec, s[0:1]
	s_waitcnt lgkmcnt(0)
	s_barrier
	ds_read_b32 v0, v1 offset:43008
	s_movk_i32 s0, 0x80
	s_waitcnt lgkmcnt(0)
	v_cmp_gt_i32_e32 vcc, s0, v0
	v_readfirstlane_b32 s18, v0
	s_mov_b64 s[0:1], -1
	s_cbranch_vccz .LBB0_515
	s_setprio 3
	s_and_saveexec_b64 s[0:1], s[6:7]
	s_cbranch_execz .LBB0_531
	s_mov_b64 s[4:5], -1
	v_mov_b32_e32 v2, v122
	v_mov_b32_e32 v0, v127
	s_and_saveexec_b64 s[2:3], s[8:9]
	s_cbranch_execz .LBB0_528
	v_readlane_b32 s20, v253, 21
	s_mov_b64 s[4:5], 0
	v_mov_b32_e32 v0, v151
	v_mov_b32_e32 v4, v153
	v_mov_b64_e32 v[2:3], v[122:123]
	v_readlane_b32 s12, v253, 5
	v_readlane_b32 s24, v253, 25
	v_readlane_b32 s25, v253, 26
	v_readlane_b32 s13, v253, 6
	v_readlane_b32 s21, v253, 22
	v_readlane_b32 s22, v253, 23
	v_readlane_b32 s23, v253, 24
	v_readlane_b32 s26, v253, 27
	v_readlane_b32 s27, v253, 28

; template <int DQK, int DV, int MODE> ...
;     ...
;   bf16_t* Qs = (bf16_t*)(smem + ATT_Q_OFF) + (w * 2 * NKS) * 512 + lane * 8;
; #pragma unroll
;   for (int qi = 0; qi < 2; ++qi)
; #pragma unroll
;     for (int ks = 0; ks < NKS; ++ks)
;       *(bf16x8*)(Qs + (qi * NKS + ks) * 512) = *(const bf16x8*)(Qp + (unsigned)((w * 32 + qi * 16 + fr) * qrs + ks * 32 + fq * 8));
; #pragma unroll
;   for (int qi = 0; qi < 2; ++qi) {
;     mrow[qi] = -1e30f; lrow[qi] = 0.f;
; #pragma unroll
;     for (int dt = 0; dt < NDT; ++dt) O[qi][dt] = (f32x4){0.f, 0.f, 0.f, 0.f};
;   }
;   int wkb, wke;
;   if (MODE == 0) { wkb = max(kt_begin, w >> 1); wke = (w * 32 + 159) / 64 + 1; }
;   else { wkb = 0; wke = (qpos0 + w * 32 + 31) / 64 + 1; }
;   u32x4 rk[NKC], rv[NVC];
;   auto gload = [&](int kt) {
; #pragma unroll
;     for (int i = 0; i < NKC; ++i) { const int c = tid + 256 * i, key = c / KCH, part = c % KCH; rk[i] = *(const u32x4*)(Kp + (unsigned)((kt * 64 + key) * krs + part * 8)); }
;     if (MODE == 0) {
; #pragma unroll
;       for (int i = 0; i < NVC; ++i) { const int c = tid + 256 * i, key = c >> 3, part = c & 7; rv[i] = *(const u32x4*)(Vp + (unsigned)((kt * 64 + key) * vrs + part * 8)); }
;     } else {
; #pragma unroll
;       for (int i = 0; i < NVC; ++i) { const int c = tid + 256 * i, dv = c >> 3, kc = c & 7; rv[i] = *(const u32x4*)(Vp + (unsigned)(dv * vrs + kt * 64 + kc * 8)); }
;     }
;   };
;   auto sstore = [&]() {
; #pragma unroll
;     for (int i = 0; i < NKC; ++i) { const int c = tid + 256 * i, key = c / KCH, part = c % KCH; *(u32x4*)(Ks + key * KST + part * 8) = rk[i]; }
;     if (MODE == 0) {
; #pragma unroll
;     ...
;     const int item = next_item(p.counters + ((cset * 4 + l) * 3 + 1) * 8 + xcd, s_item, tid);
;     if (item >= 96) break;
;     const int lvl = item / 3, sel = item % 3;
;     int bh, qb;
;     if (sel < 2) { bh = xcd; qb = 63 - 2 * lvl - sel; } else { bh = 8 + (xcd >> 1); qb = 63 - 2 * lvl - (xcd & 1); }
;     const int b = bh / 6, h = bh % 6;
;     const long tok0 = (long)b * SEQ + qb * 128;
;     const int kt_end = (qb * 128 + 127) / 64 + 1;
;     f32x4 O[2][4]; float mr[2], lr[2];
;     flash_block<96, 64, 2>(p.cq + tok0 * 576 + h * 96, 576, p.kC + (long)b * SEQ * 576 + h * 96, 576, p.vtC + (size_t)((b * 6 + h) * 64) * SEQ, SEQ,
;                            0, kt_end, qb * 128, 0, 0.10206207261596575f * LOG2E, smem, O, mr, lr, tid);
.LBB0_557:
	s_or_b64 exec, exec, s[0:1]
	s_waitcnt lgkmcnt(0)
	s_barrier
	ds_read_b32 v0, v1 offset:43008
	s_movk_i32 s0, 0x60
	s_waitcnt lgkmcnt(0)
	v_cmp_gt_i32_e32 vcc, s0, v0
	v_readfirstlane_b32 s2, v0
	s_mov_b64 s[0:1], -1
	s_cbranch_vccz .LBB0_552
	s_setprio 2
	s_mul_hi_i32 s0, s2, 0x55555556
	s_lshr_b32 s1, s0, 31
	s_add_i32 s0, s0, s1
	s_mul_i32 s1, s0, 3
	s_sub_i32 s1, s2, s1
	s_lshl_b32 s0, s0, 1
	v_readlane_b32 s3, v252, 46
	s_add_i32 s2, s0, s1
	s_or_b32 s0, s0, s3
	s_cmp_lt_i32 s1, 2
	s_cselect_b32 s0, s2, s0
	v_readlane_b32 s1, v253, 13
	v_readlane_b32 s2, v252, 45
	s_cselect_b32 s2, s1, s2
	s_mul_hi_u32 s3, s2, 0x2aaaaaab
	s_mul_i32 s1, s3, 6
	s_lshl_b32 s0, s0, 7
	s_sub_i32 s14, s2, s1
	s_lshl_b32 s1, s3, 13
	s_sub_i32 s6, 0x1f80, s0
	s_add_u32 s10, s1, s6
	s_addc_u32 s11, 0, 0
	s_sub_i32 s0, 0x1fc0, s0
	s_lshr_b32 s16, s0, 6
	s_mul_i32 s0, s11, 0x480
	s_mul_hi_u32 s1, s10, 0x480
	s_add_i32 s1, s1, s0
	s_mul_i32 s0, s10, 0x480
	s_add_u32 s4, s80, s0
	s_mul_i32 s74, s14, 0x60
	s_addc_u32 s5, s81, s1
	s_lshl_b64 s[0:1], s[74:75], 1
	s_add_u32 s4, s4, s0
	s_addc_u32 s5, s5, s1
	s_waitcnt vmcnt(0)
	v_lshl_add_u64 v[2:3], v[88:89], 1, s[4:5]
	v_lshl_add_u64 v[26:27], v[90:91], 1, s[4:5]
	v_lshl_add_u64 v[30:31], v[92:93], 1, s[4:5]
	v_lshl_add_u64 v[38:39], v[94:95], 1, s[4:5]
	global_load_dwordx4 v[22:25], v[2:3], off offset:64
	global_load_dwordx4 v[2:5], v[2:3], off
	global_load_dwordx4 v[26:29], v[26:27], off
	global_load_dwordx4 v[34:37], v[30:31], off offset:64
	global_load_dwordx4 v[30:33], v[30:31], off
	global_load_dwordx4 v[38:41], v[38:39], off
	s_mul_i32 s3, s3, 0x900000
	s_add_u32 s3, s82, s3
	s_addc_u32 s7, s83, 0
	s_add_u32 s0, s3, s0
	s_addc_u32 s1, s7, s1
	s_lshl_b32 s2, s2, 20
	s_add_u32 s2, s84, s2
	s_addc_u32 s3, s85, 0
	v_lshl_add_u64 v[14:15], v[136:137], 1, s[2:3]
	v_lshl_add_u64 v[18:19], v[138:139], 1, s[2:3]
	v_lshl_add_u64 v[10:11], v[100:101], 1, s[0:1]
	global_load_dwordx4 v[14:17], v[14:15], off
	v_add_u32_e32 v170, s6, v212
	global_load_dwordx4 v[18:21], v[18:19], off
	v_ashrrev_i32_e32 v0, 31, v170
	global_load_dwordx4 v[10:13], v[10:11], off
	v_lshl_add_u64 v[6:7], v[98:99], 1, s[0:1]
	v_lshl_add_u64 v[42:43], v[96:97], 1, s[0:1]
	global_load_dwordx4 v[6:9], v[6:7], off
	global_load_dwordx4 v[42:45], v[42:43], off
	v_lshrrev_b32_e32 v0, 26, v0
	v_add3_u32 v0, v0, v170, 31
	v_ashrrev_i32_e32 v171, 6, v0
	v_add_u32_e32 v172, 0x3800, v214
	v_add_u32_e32 v173, 0x3800, v215
	v_or_b32_e32 v0, s6, v209
	v_add_u32_e32 v102, v0, v212
	v_or_b32_e32 v167, 16, v102
	v_mov_b32_e32 v103, v102
	v_add_u32_e32 v105, 13, v102
	v_add_u32_e32 v104, 14, v102
	s_mov_b32 s17, 0
	v_mov_b32_e32 v166, 0xf149f2ca
	v_mov_b32_e32 v165, 0
	s_mov_b32 s15, 63
	v_mov_b32_e32 v0, v164
	v_mov_b32_e32 v106, v163
	v_mov_b32_e32 v108, v162
	v_mov_b32_e32 v168, 0
	v_mov_b32_e32 v169, 0xf149f2ca
	s_waitcnt vmcnt(10)
	ds_write_b128 v152, v[22:25] offset:44096
	s_waitcnt vmcnt(9)
	ds_write_b128 v152, v[2:5] offset:43072
	s_waitcnt vmcnt(8)
	ds_write_b128 v152, v[26:29] offset:45120
	s_waitcnt vmcnt(7)
	ds_write_b128 v152, v[34:37] offset:47168
	s_waitcnt vmcnt(6)
	ds_write_b128 v152, v[30:33] offset:46144
	s_waitcnt vmcnt(5)
	ds_write_b128 v152, v[38:41] offset:48192
	s_waitcnt lgkmcnt(0)
	s_barrier
	s_waitcnt vmcnt(0)
	ds_write_b128 v154, v[42:45]
	ds_write_b128 v155, v[6:9]
	ds_write_b128 v156, v[10:13]
	v_mov_b32_e32 v4, v1
	v_mov_b32_e32 v5, v1
	ds_write2_b64 v172, v[14:15], v[16:17] offset1:2
	ds_write2_b64 v173, v[18:19], v[20:21] offset1:2
	v_mov_b32_e32 v2, v1
	v_mov_b32_e32 v3, v1
	v_mov_b64_e32 v[8:9], v[4:5]
	v_mov_b64_e32 v[12:13], v[4:5]
	v_mov_b64_e32 v[16:17], v[4:5]
	v_mov_b64_e32 v[20:21], v[4:5]
	v_mov_b64_e32 v[24:25], v[4:5]
	v_mov_b64_e32 v[28:29], v[4:5]
	v_mov_b64_e32 v[32:33], v[4:5]
	v_mov_b64_e32 v[6:7], v[2:3]
	v_mov_b64_e32 v[10:11], v[2:3]
	v_mov_b64_e32 v[14:15], v[2:3]
	v_mov_b64_e32 v[18:19], v[2:3]
	v_mov_b64_e32 v[22:23], v[2:3]
	v_mov_b64_e32 v[26:27], v[2:3]
	v_mov_b64_e32 v[30:31], v[2:3]
	s_waitcnt lgkmcnt(0)
	s_barrier
	s_branch .LBB0_561
